# NA loop: K and V fragment LDS reads all issued at the top of the iteration (PV MFMAs no longer wait on LDS)
# speedup vs baseline: 1.0038x; 1.0038x over previous
; #define MFMA32(a, b, c) __builtin_amdgcn_mfma_f32_32x32x16_bf16(__builtin_bit_cast(bf16x8, (a)), __builtin_bit_cast(bf16x8, (b)), (c), 0, 0, 0)
; DI int crow(int reg, int h) { return (reg & 3) + 8 * (reg >> 2) + 4 * h; }
; template <int DQK, bool NA>
; DI void attn_unit(const bf16_t* __restrict__ Qb, int ldq, const bf16_t* __restrict__ Kb, int ldk, const bf16_t* __restrict__ Vt,
;                   bf16_t* __restrict__ Ob, int ldo, int u, float sc, const float* __restrict__ rpb_h, char* smem) {
;     ...
;     if (NA) active = (kt >= rs) && (kt < rs + 8);
;     if (active) {
;       const bf16_t* cK = sK + cur * 64 * KS + r * KS + 8 * h;
;       const bf16_t* cV = sV + cur * 64 * 72 + r * 72 + 8 * h;
;       f32x16 s0, s1;
;       {
;         const f32x16 zero16 = {0.f, 0.f, 0.f, 0.f, 0.f, 0.f, 0.f, 0.f, 0.f, 0.f, 0.f, 0.f, 0.f, 0.f, 0.f, 0.f};
;         u32x4 k0 = *(const u32x4*)(cK);
;         u32x4 k1 = *(const u32x4*)(cK + 32 * KS);
;         s0 = MFMA32(k0, qf[0], zero16);
;         s1 = MFMA32(k1, qf[0], zero16);
;       }
; #pragma unroll
;       for (int ds = 1; ds < NDS; ++ds) {
;         u32x4 k0 = *(const u32x4*)(cK + ds * 16);
;         u32x4 k1 = *(const u32x4*)(cK + 32 * KS + ds * 16);
;         s0 = MFMA32(k0, qf[ds], s0);
;         s1 = MFMA32(k1, qf[ds], s1);
;       }
;       if (NA) {
;         const int brow = (kt - rq + 7) * 31;
; #pragma unroll
;         for (int q = 0; q < 16; ++q) {
;           int kc0 = crow(q, h), kc1 = 32 + kc0;
;           bool v0 = (kc0 >= cs) && (kc0 < cs + 16), v1 = (kc1 >= cs) && (kc1 < cs + 16);
;           float b0 = v0 ? sBias[brow + kc0 - cq + 15] : 0.f;
;           float b1 = v1 ? sBias[brow + kc1 - cq + 15] : 0.f;
;           s0[q] = v0 ? (s0[q] * sc + b0) : -INFINITY;
;           s1[q] = v1 ? (s1[q] * sc + b1) : -INFINITY;
;         }
;       }
;       float mx = s0[0];
; #pragma unroll
;       for (int q = 1; q < 16; ++q) mx = fmaxf(mx, s0[q]);
; #pragma unroll
;       for (int q = 0; q < 16; ++q) mx = fmaxf(mx, s1[q]);
;       mx = fmaxf(mx, __shfl_xor(mx, 32));
;       if (__builtin_amdgcn_ballot_w64((mx - m_run) > 8.f) != 0ull) {
.LBB0_296:
	v_cmp_ge_u32_e32 vcc, s97, v137
	v_cmp_lt_u32_e64 s[88:89], s97, v138
	s_and_b32 s1, s97, 1
	s_and_b64 vcc, vcc, s[88:89]
	s_and_saveexec_b64 s[88:89], vcc
	s_cbranch_execz .LBB0_360
	s_mul_i32 s4, s1, 0x2400
	v_add_u32_e32 v0, s4, v139
	ds_read_b128 v[160:163], v0
	ds_read_b128 v[164:167], v0 offset:4608
	ds_read_b128 v[168:171], v0 offset:32
	ds_read_b128 v[172:175], v0 offset:4640
	ds_read_b128 v[176:179], v0 offset:64
	ds_read_b128 v[180:183], v0 offset:4672
	ds_read_b128 v[184:187], v0 offset:96
	ds_read_b128 v[188:191], v0 offset:4704
	ds_read_b128 v[192:195], v0 offset:18432
	ds_read_b128 v[198:201], v0 offset:23040
	ds_read_b128 v[202:205], v0 offset:18464
	ds_read_b128 v[206:209], v0 offset:23072
	ds_read_b128 v[210:213], v0 offset:18496
	ds_read_b128 v[214:217], v0 offset:23104
	ds_read_b128 v[218:221], v0 offset:18528
	ds_read_b128 v[222:225], v0 offset:23136
	s_waitcnt lgkmcnt(15)
	v_mfma_f32_32x32x16_bf16 v[64:79], v[160:163], v[80:83], 0
	s_waitcnt lgkmcnt(14)
	v_mfma_f32_32x32x16_bf16 v[48:63], v[164:167], v[80:83], 0
	s_waitcnt lgkmcnt(13)
	v_mfma_f32_32x32x16_bf16 v[64:79], v[168:171], v[84:87], v[64:79]
	s_waitcnt lgkmcnt(12)
	v_mfma_f32_32x32x16_bf16 v[48:63], v[172:175], v[84:87], v[48:63]
	s_waitcnt lgkmcnt(11)
	v_mfma_f32_32x32x16_bf16 v[64:79], v[176:179], v[88:91], v[64:79]
	s_waitcnt lgkmcnt(10)
	v_mfma_f32_32x32x16_bf16 v[48:63], v[180:183], v[88:91], v[48:63]
	s_waitcnt lgkmcnt(9)
	v_mfma_f32_32x32x16_bf16 v[64:79], v[184:187], v[92:95], v[64:79]
	s_waitcnt lgkmcnt(8)
	v_mfma_f32_32x32x16_bf16 v[48:63], v[188:191], v[92:95], v[48:63]
	ds_read_b32 v3, v141
	ds_read_b32 v117, v141 offset:128
	ds_read_b32 v5, v141 offset:4
	ds_read_b32 v142, v141 offset:132
	ds_read_b32 v143, v141 offset:8
	ds_read_b32 v144, v141 offset:136
	ds_read_b32 v145, v141 offset:12
	ds_read_b32 v146, v141 offset:140
	ds_read_b32 v147, v141 offset:32
	ds_read_b32 v148, v141 offset:160
	ds_read_b32 v149, v141 offset:36
	ds_read_b32 v150, v141 offset:164
	ds_read_b32 v151, v141 offset:40
	ds_read_b32 v152, v141 offset:168
	ds_read_b32 v153, v141 offset:44
	ds_read_b32 v154, v141 offset:172
	ds_read_b32 v14, v141 offset:64
	ds_read_b32 v155, v141 offset:192
	ds_read_b32 v15, v141 offset:68
	ds_read_b32 v156, v141 offset:196
	ds_read_b32 v10, v141 offset:72
	ds_read_b32 v12, v141 offset:200
	ds_read_b32 v11, v141 offset:76
	ds_read_b32 v13, v141 offset:204
	ds_read_b32 v6, v141 offset:96
	ds_read_b32 v8, v141 offset:224
	ds_read_b32 v7, v141 offset:100
	ds_read_b32 v9, v141 offset:228
	ds_read_b32 v2, v141 offset:104
	ds_read_b32 v4, v141 offset:232
	ds_read_b32 v157, v141 offset:108
	ds_read_b32 v158, v141 offset:236
	s_waitcnt lgkmcnt(0)
	v_fmac_f32_e32 v5, 0x3e38aa3b, v65
	v_fmac_f32_e32 v3, 0x3e38aa3b, v64
	v_fmac_f32_e32 v145, 0x3e38aa3b, v67
	v_fmac_f32_e32 v143, 0x3e38aa3b, v66
	v_cndmask_b32_e64 v65, v5, v129, s[10:11]
	v_cndmask_b32_e64 v64, v3, v129, s[6:7]
	v_fmac_f32_e32 v4, 0x3e38aa3b, v62
	v_fmac_f32_e32 v149, 0x3e38aa3b, v69
	v_fmac_f32_e32 v147, 0x3e38aa3b, v68
	v_cndmask_b32_e64 v67, v145, v129, s[22:23]
	v_cndmask_b32_e64 v66, v143, v129, s[16:17]
	v_max_f32_e32 v62, v64, v65
	v_fmac_f32_e32 v9, 0x3e38aa3b, v61
	v_fmac_f32_e32 v8, 0x3e38aa3b, v60
	v_fmac_f32_e32 v153, 0x3e38aa3b, v71
	v_fmac_f32_e32 v151, 0x3e38aa3b, v70
	v_cndmask_b32_e64 v61, v149, v129, s[36:37]
	v_cndmask_b32_e64 v60, v147, v129, s[28:29]
	v_max3_f32 v62, v62, v66, v67
	v_fmac_f32_e32 v13, 0x3e38aa3b, v59
	v_fmac_f32_e32 v12, 0x3e38aa3b, v58
	v_fmac_f32_e32 v15, 0x3e38aa3b, v73
	v_fmac_f32_e32 v14, 0x3e38aa3b, v72
	v_cndmask_b32_e64 v59, v153, v129, s[48:49]
	v_cndmask_b32_e64 v58, v151, v129, s[42:43]
	v_max3_f32 v62, v62, v60, v61
	v_fmac_f32_e32 v11, 0x3e38aa3b, v75
	v_fmac_f32_e32 v10, 0x3e38aa3b, v74
	v_cndmask_b32_e64 v15, v129, v15, s[58:59]
	v_cndmask_b32_e64 v14, v129, v14, s[54:55]
	v_max3_f32 v62, v62, v58, v59
	v_fmac_f32_e32 v7, 0x3e38aa3b, v77
	v_fmac_f32_e32 v6, 0x3e38aa3b, v76
	v_cndmask_b32_e64 v11, v129, v11, s[66:67]
	v_cndmask_b32_e64 v10, v129, v10, s[62:63]
	v_max3_f32 v62, v62, v14, v15
	v_fmac_f32_e32 v2, 0x3e38aa3b, v78
	v_cndmask_b32_e64 v7, v129, v7, s[74:75]
	v_cndmask_b32_e64 v6, v129, v6, s[70:71]
	v_fmac_f32_e32 v157, 0x3e38aa3b, v79
	v_max3_f32 v62, v62, v10, v11
	v_cndmask_b32_e64 v2, v129, v2, s[78:79]
	v_fmac_f32_e32 v142, 0x3e38aa3b, v49
	v_fmac_f32_e32 v117, 0x3e38aa3b, v48
	v_cndmask_b32_e64 v3, v129, v157, s[80:81]
	v_max3_f32 v62, v62, v6, v7
	v_fmac_f32_e32 v146, 0x3e38aa3b, v51
	v_fmac_f32_e32 v144, 0x3e38aa3b, v50
	v_cndmask_b32_e64 v49, v129, v142, s[14:15]
	v_cndmask_b32_e64 v48, v129, v117, s[8:9]
	v_max3_f32 v62, v62, v2, v3
	v_fmac_f32_e32 v150, 0x3e38aa3b, v53
	v_fmac_f32_e32 v148, 0x3e38aa3b, v52
	v_cndmask_b32_e64 v51, v129, v146, s[26:27]
	v_cndmask_b32_e64 v50, v129, v144, s[20:21]
	v_max3_f32 v62, v62, v48, v49
	v_fmac_f32_e32 v154, 0x3e38aa3b, v55
	v_fmac_f32_e32 v152, 0x3e38aa3b, v54
	v_cndmask_b32_e64 v53, v129, v150, s[40:41]
	v_cndmask_b32_e64 v52, v129, v148, s[34:35]
	v_max3_f32 v62, v62, v50, v51
	v_fmac_f32_e32 v156, 0x3e38aa3b, v57
	v_fmac_f32_e32 v155, 0x3e38aa3b, v56
	v_cndmask_b32_e64 v55, v129, v154, s[52:53]
	v_cndmask_b32_e64 v54, v129, v152, s[46:47]
	v_max3_f32 v62, v62, v52, v53
	v_cndmask_b32_e64 v57, v129, v156, s[60:61]
	v_cndmask_b32_e64 v56, v129, v155, s[56:57]
	v_max3_f32 v62, v62, v54, v55
	v_and_b32_e32 v68, 64, v197
	v_cndmask_b32_e64 v13, v129, v13, s[68:69]
	v_cndmask_b32_e64 v12, v129, v12, s[64:65]
	v_fmac_f32_e32 v158, 0x3e38aa3b, v63
	v_max3_f32 v62, v62, v56, v57
	v_xor_b32_e32 v63, 32, v197
	v_add_u32_e32 v68, 64, v68
	v_cndmask_b32_e64 v9, v129, v9, s[76:77]
	v_cndmask_b32_e64 v8, v129, v8, s[72:73]
	v_max3_f32 v62, v62, v12, v13
	v_cmp_lt_i32_e32 vcc, v63, v68
	v_cndmask_b32_e64 v4, v129, v4, s[82:83]
	v_cndmask_b32_e64 v5, v129, v158, s[84:85]
	v_max3_f32 v62, v62, v8, v9
	v_cndmask_b32_e32 v63, v197, v63, vcc
	v_max3_f32 v62, v62, v4, v5
	v_lshlrev_b32_e32 v63, 2, v63
	ds_bpermute_b32 v63, v63, v62
	s_waitcnt lgkmcnt(0)
	v_max_f32_e32 v63, v63, v63
	v_max_f32_e32 v62, v62, v63
	v_sub_f32_e32 v63, v62, v124
	v_cmp_lt_f32_e32 vcc, s0, v63
	s_cbranch_vccz .LBB0_359
; #define MFMA32(a, b, c) __builtin_amdgcn_mfma_f32_32x32x16_bf16(__builtin_bit_cast(bf16x8, (a)), __builtin_bit_cast(bf16x8, (b)), (c), 0, 0, 0)
; DI unsigned pack2(float a, float b) { f2_t f = {a, b}; bf2_t r = __builtin_convertvector(f, bf2_t); return __builtin_bit_cast(unsigned, r); }
; DI float ex2(float x) { return __builtin_amdgcn_exp2f(x); }
; template <int DQK, bool NA>
; DI void attn_unit(const bf16_t* __restrict__ Qb, int ldq, const bf16_t* __restrict__ Kb, int ldk, const bf16_t* __restrict__ Vt,
;                   bf16_t* __restrict__ Ob, int ldo, int u, float sc, const float* __restrict__ rpb_h, char* smem) {
;     ...
;       if (__builtin_amdgcn_ballot_w64((mx - m_run) > 8.f) != 0ull) {
;         const float m_new = fmaxf(m_run, mx);
;         const float alpha = ex2(m_run - m_new);
;         m_run = m_new;
;         l_run *= alpha;
; #pragma unroll
;         for (int q = 0; q < 16; ++q) { o0[q] *= alpha; o1[q] *= alpha; }
;       }
;       const f2_t nm = {-m_run, -m_run};
;       f2_t ls2 = {0.f, 0.f};
; #pragma unroll
;       for (int q = 0; q < 16; q += 2) {
;         f2_t a = {s0[q], s0[q + 1]}, b = {s1[q], s1[q + 1]};
;         a = a + nm; b = b + nm;
;         a[0] = ex2(a[0]); a[1] = ex2(a[1]); b[0] = ex2(b[0]); b[1] = ex2(b[1]);
;         s0[q] = a[0]; s0[q + 1] = a[1]; s1[q] = b[0]; s1[q + 1] = b[1];
;         ls2 = ls2 + a; ls2 = ls2 + b;
;       }
;       l_run += ls2[0] + ls2[1];
;       u32x4 pf[4];
; #pragma unroll
;       for (int s = 0; s < 2; ++s) {
;         pf[s][0] = pack2(s0[8 * s], s0[8 * s + 1]); pf[s][1] = pack2(s0[8 * s + 2], s0[8 * s + 3]);
;         pf[s][2] = pack2(s0[8 * s + 4], s0[8 * s + 5]); pf[s][3] = pack2(s0[8 * s + 6], s0[8 * s + 7]);
;         pf[2 + s][0] = pack2(s1[8 * s], s1[8 * s + 1]); pf[2 + s][1] = pack2(s1[8 * s + 2], s1[8 * s + 3]);
;         pf[2 + s][2] = pack2(s1[8 * s + 4], s1[8 * s + 5]); pf[2 + s][3] = pack2(s1[8 * s + 6], s1[8 * s + 7]);
;       }
; #pragma unroll
;       for (int ks = 0; ks < 4; ++ks) {
;         u32x4 v0 = *(const u32x4*)(cV + ks * 16);
;         u32x4 v1 = *(const u32x4*)(cV + 32 * 72 + ks * 16);
;         o0 = MFMA32(v0, pf[ks], o0);
;         o1 = MFMA32(v1, pf[ks], o1);
;       }
	v_max_f32_e32 v62, v62, v62
	v_max_f32_e32 v63, v124, v124
	v_max_f32_e32 v63, v63, v62
	v_sub_f32_e32 v62, v124, v63
	v_exp_f32_e32 v62, v62
	v_mov_b32_e32 v124, v63
	v_pk_mul_f32 v[46:47], v[46:47], v[62:63] op_sel_hi:[1,0]
	v_pk_mul_f32 v[44:45], v[44:45], v[62:63] op_sel_hi:[1,0]
	v_pk_mul_f32 v[42:43], v[42:43], v[62:63] op_sel_hi:[1,0]
	v_pk_mul_f32 v[40:41], v[40:41], v[62:63] op_sel_hi:[1,0]
	v_pk_mul_f32 v[38:39], v[38:39], v[62:63] op_sel_hi:[1,0]
	v_pk_mul_f32 v[36:37], v[36:37], v[62:63] op_sel_hi:[1,0]
	v_pk_mul_f32 v[34:35], v[34:35], v[62:63] op_sel_hi:[1,0]
	v_pk_mul_f32 v[32:33], v[32:33], v[62:63] op_sel_hi:[1,0]
	v_pk_mul_f32 v[30:31], v[30:31], v[62:63] op_sel_hi:[1,0]
	v_pk_mul_f32 v[28:29], v[28:29], v[62:63] op_sel_hi:[1,0]
	v_pk_mul_f32 v[26:27], v[26:27], v[62:63] op_sel_hi:[1,0]
	v_pk_mul_f32 v[24:25], v[24:25], v[62:63] op_sel_hi:[1,0]
	v_pk_mul_f32 v[22:23], v[22:23], v[62:63] op_sel_hi:[1,0]
	v_pk_mul_f32 v[20:21], v[20:21], v[62:63] op_sel_hi:[1,0]
	v_pk_mul_f32 v[18:19], v[18:19], v[62:63] op_sel_hi:[1,0]
	v_pk_mul_f32 v[16:17], v[16:17], v[62:63] op_sel_hi:[1,0]
	v_mul_f32_e32 v140, v140, v62
.LBB0_359:
	v_pk_add_f32 v[62:63], v[64:65], v[124:125] op_sel_hi:[1,0] neg_lo:[0,1] neg_hi:[0,1]
	v_pk_add_f32 v[48:49], v[48:49], v[124:125] op_sel_hi:[1,0] neg_lo:[0,1] neg_hi:[0,1]
	v_exp_f32_e32 v62, v62
	v_exp_f32_e32 v63, v63
	v_exp_f32_e32 v64, v48
	v_exp_f32_e32 v65, v49
	v_pk_add_f32 v[66:67], v[66:67], v[124:125] op_sel_hi:[1,0] neg_lo:[0,1] neg_hi:[0,1]
	v_pk_add_f32 v[50:51], v[50:51], v[124:125] op_sel_hi:[1,0] neg_lo:[0,1] neg_hi:[0,1]
	v_exp_f32_e32 v66, v66
	v_exp_f32_e32 v67, v67
	v_exp_f32_e32 v68, v50
	v_exp_f32_e32 v69, v51
	v_pk_add_f32 v[50:51], v[60:61], v[124:125] op_sel_hi:[1,0] neg_lo:[0,1] neg_hi:[0,1]
	v_pk_add_f32 v[52:53], v[52:53], v[124:125] op_sel_hi:[1,0] neg_lo:[0,1] neg_hi:[0,1]
	v_exp_f32_e32 v50, v50
	v_exp_f32_e32 v51, v51
	v_pk_add_f32 v[48:49], v[64:65], v[62:63]
	v_exp_f32_e32 v52, v52
	v_exp_f32_e32 v53, v53
	v_pk_add_f32 v[58:59], v[58:59], v[124:125] op_sel_hi:[1,0] neg_lo:[0,1] neg_hi:[0,1]
	v_pk_add_f32 v[48:49], v[66:67], v[48:49]
	v_pk_add_f32 v[54:55], v[54:55], v[124:125] op_sel_hi:[1,0] neg_lo:[0,1] neg_hi:[0,1]
	v_exp_f32_e32 v58, v58
	v_exp_f32_e32 v59, v59
	v_pk_add_f32 v[48:49], v[68:69], v[48:49]
	v_exp_f32_e32 v54, v54
	v_exp_f32_e32 v55, v55
	v_pk_add_f32 v[14:15], v[14:15], v[124:125] op_sel_hi:[1,0] neg_lo:[0,1] neg_hi:[0,1]
	v_pk_add_f32 v[48:49], v[50:51], v[48:49]
	v_pk_add_f32 v[56:57], v[56:57], v[124:125] op_sel_hi:[1,0] neg_lo:[0,1] neg_hi:[0,1]
	v_exp_f32_e32 v14, v14
	v_exp_f32_e32 v15, v15
	v_pk_add_f32 v[48:49], v[52:53], v[48:49]
	v_exp_f32_e32 v56, v56
	v_exp_f32_e32 v57, v57
	v_pk_add_f32 v[10:11], v[10:11], v[124:125] op_sel_hi:[1,0] neg_lo:[0,1] neg_hi:[0,1]
	v_pk_add_f32 v[48:49], v[58:59], v[48:49]
	v_pk_add_f32 v[12:13], v[12:13], v[124:125] op_sel_hi:[1,0] neg_lo:[0,1] neg_hi:[0,1]
	v_exp_f32_e32 v60, v10
	v_exp_f32_e32 v61, v11
	v_pk_add_f32 v[48:49], v[54:55], v[48:49]
	v_exp_f32_e32 v70, v12
	v_exp_f32_e32 v71, v13
	v_pk_add_f32 v[6:7], v[6:7], v[124:125] op_sel_hi:[1,0] neg_lo:[0,1] neg_hi:[0,1]
	v_pk_add_f32 v[48:49], v[14:15], v[48:49]
	v_pk_add_f32 v[8:9], v[8:9], v[124:125] op_sel_hi:[1,0] neg_lo:[0,1] neg_hi:[0,1]
	v_exp_f32_e32 v12, v6
	v_exp_f32_e32 v13, v7
	v_pk_add_f32 v[48:49], v[56:57], v[48:49]
	v_exp_f32_e32 v72, v8
	v_exp_f32_e32 v73, v9
	v_pk_add_f32 v[2:3], v[2:3], v[124:125] op_sel_hi:[1,0] neg_lo:[0,1] neg_hi:[0,1]
	v_pk_add_f32 v[10:11], v[60:61], v[48:49]
	v_exp_f32_e32 v2, v2
	v_exp_f32_e32 v3, v3
	v_pk_add_f32 v[10:11], v[70:71], v[10:11]
	v_pk_add_f32 v[4:5], v[4:5], v[124:125] op_sel_hi:[1,0] neg_lo:[0,1] neg_hi:[0,1]
	v_pk_add_f32 v[6:7], v[12:13], v[10:11]
	v_exp_f32_e32 v74, v4
	v_pk_add_f32 v[6:7], v[72:73], v[6:7]
	v_exp_f32_e32 v75, v5
	v_pk_add_f32 v[4:5], v[2:3], v[6:7]
	v_cvt_pk_bf16_f32 v48, v62, v63
	v_cvt_pk_bf16_f32 v50, v50, v51
	v_cvt_pk_bf16_f32 v51, v58, v59
	v_cvt_pk_bf16_f32 v8, v52, v53
	v_cvt_pk_bf16_f32 v9, v54, v55
	v_cvt_pk_bf16_f32 v11, v60, v61
	v_cvt_pk_bf16_f32 v12, v12, v13
	v_cvt_pk_bf16_f32 v13, v2, v3
	v_cvt_pk_bf16_f32 v2, v56, v57
	v_cvt_pk_bf16_f32 v49, v66, v67
	v_cvt_pk_bf16_f32 v10, v14, v15
	v_cvt_pk_bf16_f32 v6, v64, v65
	s_nop 0
	v_mfma_f32_32x32x16_bf16 v[32:47], v[192:195], v[48:51], v[32:47]
	v_cvt_pk_bf16_f32 v7, v68, v69
	v_add_f32_e64 v4, v74, v4
	v_add_f32_e64 v5, v75, v5
	v_cvt_pk_bf16_f32 v3, v70, v71
	v_add_f32_e32 v76, v4, v5
	v_cvt_pk_bf16_f32 v4, v72, v73
	v_cvt_pk_bf16_f32 v5, v74, v75
	v_add_f32_e32 v140, v140, v76
	v_mfma_f32_32x32x16_bf16 v[16:31], v[198:201], v[48:51], v[16:31]
	s_nop 0
	v_mfma_f32_32x32x16_bf16 v[32:47], v[202:205], v[10:13], v[32:47]
	s_nop 0
	v_mfma_f32_32x32x16_bf16 v[16:31], v[206:209], v[10:13], v[16:31]
	s_nop 0
	v_mfma_f32_32x32x16_bf16 v[32:47], v[210:213], v[6:9], v[32:47]
	s_nop 0
	v_mfma_f32_32x32x16_bf16 v[16:31], v[214:217], v[6:9], v[16:31]
	s_nop 0
	v_mfma_f32_32x32x16_bf16 v[32:47], v[218:221], v[2:5], v[32:47]
	s_nop 0
	v_mfma_f32_32x32x16_bf16 v[16:31], v[222:225], v[2:5], v[16:31]
